# group barrier also between FF1 and FF2 of layer 0 (waits for the panel whose h2 / merged rows the FF2 epilogue's h rows overlay)
# speedup vs baseline: 1.0303x; 1.0031x over previous
.Lrp_done:
	s_cmp_eq_u32 s14, 11
	s_cbranch_scc1 .LBB0_681
	s_cmp_ge_i32 s17, s15
	s_cbranch_scc1 .LBB0_681
	v_readlane_b32 s99, v255, 59
	s_lshr_b32 s98, 0x160580, s14
	s_and_b32 s98, s98, s99
	s_bitcmp1_b32 s98, 0
	s_cbranch_scc0 .Lgg_no
	s_waitcnt vmcnt(0)
	s_barrier
	s_and_saveexec_b64 s[2:3], s[86:87]
	s_cbranch_execz .Lgg_join
	v_readlane_b32 s6, v253, 55
	s_and_b32 s7, s6, 7
	s_lshl_b32 s7, s7, 3
	s_bfe_u32 s6, s6, 0x30003
	s_add_i32 s6, s6, s7
	s_lshl_b32 s7, s6, 8
	s_add_i32 s7, s7, 0x4040
	s_cmp_eq_u32 s14, 18
	s_cselect_b32 s8, 4, 0
	s_cmp_eq_u32 s14, 20
	s_cselect_b32 s8, 8, s8
	s_cmp_eq_u32 s14, 7
	s_cselect_b32 s8, 12, s8
	s_cmp_eq_u32 s14, 17
	s_cselect_b32 s8, 16, s8
	s_cmp_eq_u32 s14, 10
	s_cselect_b32 s8, 20, s8
	s_add_i32 s8, s7, s8
	v_mov_b32_e32 v20, s8
	s_mov_b32 s9, s8
	s_mov_b32 s10, 0
	s_cmp_eq_u32 s14, 8
	s_cselect_b32 s11, 1, 0
	s_cmp_eq_u32 s14, 18
	s_cselect_b32 s11, 1, s11
	s_cmp_lt_u32 s6, 48
	s_cselect_b32 s11, s11, 0
	s_cmp_eq_u32 s11, 1
	s_cbranch_scc0 .Lgg_d1
	s_lshl_b32 s9, s6, 2
	s_and_b32 s9, s9, 63
	s_lshl_b32 s9, s9, 8
	s_add_i32 s9, s9, 0x404c
	s_cmp_eq_u32 s14, 18
	s_cselect_b32 s10, 4, 0
	s_add_i32 s9, s9, s10
	s_movk_i32 s10, 0x100
.Lgg_d1:
	s_cmp_eq_u32 s14, 10
	s_cbranch_scc0 .Lgg_d2
	s_add_i32 s9, s6, 42
	s_lshl_b32 s9, s9, 8
	s_add_i32 s9, s9, 0x4054
	s_add_i32 s11, s6, -22
	s_lshl_b32 s11, s11, 8
	s_add_i32 s11, s11, 0x4040
	s_cmp_lt_u32 s6, 22
	s_cselect_b32 s9, s9, s11
.Lgg_d2:
	v_mov_b32_e32 v21, s9
	s_add_i32 s9, s9, s10
	v_mov_b32_e32 v23, s9
	s_add_i32 s9, s9, s10
	v_mov_b32_e32 v24, s9
	s_add_i32 s9, s9, s10
	v_mov_b32_e32 v25, s9
	s_mov_b32 s58, 0
	global_atomic_add v20, v202, s[12:13]
